# v6 + ResNorm epilogue: residual-stream stores issued after the slot exchange instead of before it
# speedup vs baseline: 1.0023x; 1.0023x over previous
.LBB0_380:
	s_cmp_gt_u32 s3, 63
	s_cbranch_scc1 .LBB0_393
	s_memrealtime s[38:39]
	s_lshl_b32 s14, s30, 6
	s_ashr_i32 s15, s14, 31
	s_lshl_b64 s[14:15], s[14:15], 2
	s_add_u32 s40, s56, s14
	s_addc_u32 s41, s57, s15
	s_mov_b32 s3, 1
	s_branch .LBB0_383

.LBB0_395:
	s_ashr_i32 s35, s34, 31
	s_lshl_b64 s[16:17], s[34:35], 13
	s_mul_hi_i32 s15, s34, 0x12000
	s_mul_i32 s14, s34, 0x12000
	s_waitcnt vmcnt(0) lgkmcnt(0)
	s_barrier
	v_lshlrev_b64 v[130:131], 13, v[178:179]
	v_lshlrev_b64 v[132:133], 13, v[180:181]
	v_lshlrev_b64 v[134:135], 13, v[182:183]
	v_lshl_add_u64 v[130:131], v[164:165], 0, v[130:131]
	global_store_dwordx4 v[130:131], v[86:89], off nt
	global_store_dwordx4 v[130:131], v[82:85], off offset:16 nt
	global_store_dwordx4 v[130:131], v[26:29], off offset:512 nt
	global_store_dwordx4 v[130:131], v[30:33], off offset:528 nt
	v_lshl_add_u64 v[130:131], v[164:165], 0, v[132:133]
	global_store_dwordx4 v[130:131], v[110:113], off nt
	global_store_dwordx4 v[130:131], v[106:109], off offset:16 nt
	global_store_dwordx4 v[130:131], v[42:45], off offset:512 nt
	global_store_dwordx4 v[130:131], v[50:53], off offset:528 nt
	v_lshl_add_u64 v[130:131], v[164:165], 0, v[134:135]
	global_store_dwordx4 v[130:131], v[118:121], off nt
	global_store_dwordx4 v[130:131], v[114:117], off offset:16 nt
	global_store_dwordx4 v[130:131], v[66:69], off offset:512 nt
	global_store_dwordx4 v[130:131], v[70:73], off offset:528 nt
	v_lshl_add_u64 v[130:131], v[164:165], 0, v[200:201]
	global_store_dwordx4 v[130:131], v[126:129], off nt
	global_store_dwordx4 v[130:131], v[122:125], off offset:16 nt
	global_store_dwordx4 v[130:131], v[90:93], off offset:512 nt
	global_store_dwordx4 v[130:131], v[94:97], off offset:528 nt
	v_lshl_add_u64 v[130:131], v[164:165], 0, v[202:203]
	global_store_dwordx4 v[130:131], v[102:105], off nt
	global_store_dwordx4 v[130:131], v[98:101], off offset:16 nt
	global_store_dwordx4 v[130:131], v[78:81], off offset:512 nt
	global_store_dwordx4 v[130:131], v[74:77], off offset:528 nt
	v_lshl_add_u64 v[130:131], v[164:165], 0, v[204:205]
	global_store_dwordx4 v[130:131], v[62:65], off nt
	global_store_dwordx4 v[130:131], v[58:61], off offset:16 nt
	global_store_dwordx4 v[130:131], v[54:57], off offset:512 nt
	global_store_dwordx4 v[130:131], v[46:49], off offset:528 nt
	v_lshl_add_u64 v[130:131], v[164:165], 0, v[206:207]
	global_store_dwordx4 v[130:131], v[38:41], off nt
	global_store_dwordx4 v[130:131], v[34:37], off offset:16 nt
	global_store_dwordx4 v[130:131], v[22:25], off offset:512 nt
	global_store_dwordx4 v[130:131], v[18:21], off offset:528 nt
	v_lshl_add_u64 v[130:131], v[164:165], 0, v[208:209]
	global_store_dwordx4 v[130:131], v[14:17], off nt
	global_store_dwordx4 v[130:131], v[10:13], off offset:16 nt
	global_store_dwordx4 v[130:131], v[6:9], off offset:512 nt
	global_store_dwordx4 v[130:131], v[2:5], off offset:528 nt
	v_lshl_add_u64 v[194:195], v[166:167], 0, s[16:17]
	v_lshl_add_u64 v[196:197], v[168:169], 0, s[14:15]
	global_load_dwordx4 v[138:141], v[194:195], off
	global_load_dwordx4 v[142:145], v[196:197], off
	global_load_dwordx4 v[130:133], v[196:197], off offset:16
	s_waitcnt lgkmcnt(0)
	global_load_dwordx4 v[134:137], v[194:195], off offset:16
	ds_read2_b32 v[198:199], v212 offset1:16
	v_lshlrev_b64 v[178:179], 12, v[178:179]
	v_lshlrev_b64 v[200:201], 12, v[180:181]
	v_lshl_add_u64 v[180:181], v[170:171], 0, v[178:179]
	v_lshl_add_u64 v[178:179], v[170:171], 0, v[200:201]
	s_waitcnt lgkmcnt(0)
	v_pk_mul_f32 v[88:89], v[88:89], v[198:199] op_sel_hi:[1,0]
	v_pk_mul_f32 v[86:87], v[86:87], v[198:199] op_sel_hi:[1,0]
	v_pk_mul_f32 v[84:85], v[84:85], v[198:199] op_sel_hi:[1,0]
	v_pk_mul_f32 v[82:83], v[82:83], v[198:199] op_sel_hi:[1,0]
	v_mov_b32_e32 v198, v199
	v_pk_mul_f32 v[112:113], v[112:113], v[198:199] op_sel_hi:[1,0]
	v_pk_mul_f32 v[110:111], v[110:111], v[198:199] op_sel_hi:[1,0]
	v_pk_mul_f32 v[108:109], v[108:109], v[198:199] op_sel_hi:[1,0]
	v_pk_mul_f32 v[106:107], v[106:107], v[198:199] op_sel_hi:[1,0]
	s_andn2_b64 vcc, exec, s[28:29]
	s_mov_b64 s[28:29], -1
	s_waitcnt vmcnt(2)
	v_pk_fma_f32 v[88:89], v[140:141], v[88:89], v[144:145]
	v_pk_fma_f32 v[86:87], v[138:139], v[86:87], v[142:143]
	s_waitcnt vmcnt(0)
	v_pk_fma_f32 v[198:199], v[136:137], v[84:85], v[132:133]
	v_pk_fma_f32 v[84:85], v[134:135], v[82:83], v[130:131]
	v_pk_fma_f32 v[112:113], v[140:141], v[112:113], v[144:145]
	v_pk_fma_f32 v[110:111], v[138:139], v[110:111], v[142:143]
	v_pk_fma_f32 v[108:109], v[136:137], v[108:109], v[132:133]
	v_pk_fma_f32 v[106:107], v[134:135], v[106:107], v[130:131]
	v_cvt_pk_bf16_f32 v82, v86, v87
	v_cvt_pk_bf16_f32 v83, v88, v89
	v_cvt_pk_bf16_f32 v84, v84, v85
	v_cvt_pk_bf16_f32 v85, v198, v199
	v_cvt_pk_bf16_f32 v86, v110, v111
	v_cvt_pk_bf16_f32 v87, v112, v113
	v_cvt_pk_bf16_f32 v88, v106, v107
	v_cvt_pk_bf16_f32 v89, v108, v109
	global_store_dwordx4 v[180:181], v[82:85], off
	global_store_dwordx4 v[178:179], v[86:89], off
	ds_read2_b32 v[86:87], v212 offset0:32 offset1:48
	v_lshlrev_b64 v[82:83], 12, v[182:183]
	v_lshlrev_b64 v[88:89], 12, v[184:185]
	v_lshl_add_u64 v[84:85], v[170:171], 0, v[82:83]
	v_lshl_add_u64 v[82:83], v[170:171], 0, v[88:89]
	s_waitcnt lgkmcnt(0)
	v_pk_mul_f32 v[88:89], v[120:121], v[86:87] op_sel_hi:[1,0]
	v_pk_mul_f32 v[106:107], v[118:119], v[86:87] op_sel_hi:[1,0]
	v_pk_mul_f32 v[108:109], v[116:117], v[86:87] op_sel_hi:[1,0]
	v_pk_mul_f32 v[110:111], v[114:115], v[86:87] op_sel_hi:[1,0]
	v_mov_b32_e32 v86, v87
	v_pk_fma_f32 v[88:89], v[140:141], v[88:89], v[144:145]
	v_pk_fma_f32 v[106:107], v[138:139], v[106:107], v[142:143]
	v_pk_fma_f32 v[108:109], v[136:137], v[108:109], v[132:133]
	v_pk_fma_f32 v[110:111], v[134:135], v[110:111], v[130:131]
	v_pk_mul_f32 v[112:113], v[128:129], v[86:87] op_sel_hi:[1,0]
	v_pk_mul_f32 v[114:115], v[126:127], v[86:87] op_sel_hi:[1,0]
	v_pk_mul_f32 v[116:117], v[124:125], v[86:87] op_sel_hi:[1,0]
	v_pk_mul_f32 v[118:119], v[122:123], v[86:87] op_sel_hi:[1,0]
	v_cvt_pk_bf16_f32 v86, v106, v107
	v_cvt_pk_bf16_f32 v87, v88, v89
	v_cvt_pk_bf16_f32 v88, v110, v111
	v_cvt_pk_bf16_f32 v89, v108, v109
	v_pk_fma_f32 v[106:107], v[140:141], v[112:113], v[144:145]
	v_pk_fma_f32 v[108:109], v[138:139], v[114:115], v[142:143]
	v_pk_fma_f32 v[110:111], v[136:137], v[116:117], v[132:133]
	v_pk_fma_f32 v[112:113], v[134:135], v[118:119], v[130:131]
	global_store_dwordx4 v[84:85], v[86:89], off
	s_nop 1
	v_cvt_pk_bf16_f32 v86, v108, v109
	v_cvt_pk_bf16_f32 v87, v106, v107
	v_cvt_pk_bf16_f32 v88, v112, v113
	v_cvt_pk_bf16_f32 v89, v110, v111
	global_store_dwordx4 v[82:83], v[86:89], off
	ds_read2_b32 v[88:89], v212 offset0:128 offset1:144
	s_waitcnt lgkmcnt(0)
	v_pk_mul_f32 v[104:105], v[104:105], v[88:89] op_sel_hi:[1,0]
	v_pk_mul_f32 v[102:103], v[102:103], v[88:89] op_sel_hi:[1,0]
	v_pk_mul_f32 v[100:101], v[100:101], v[88:89] op_sel_hi:[1,0]
	v_pk_mul_f32 v[98:99], v[98:99], v[88:89] op_sel_hi:[1,0]
	v_mov_b32_e32 v88, v89
	v_lshlrev_b64 v[86:87], 12, v[186:187]
	v_pk_fma_f32 v[104:105], v[140:141], v[104:105], v[144:145]
	v_pk_fma_f32 v[102:103], v[138:139], v[102:103], v[142:143]
	v_pk_fma_f32 v[100:101], v[136:137], v[100:101], v[132:133]
	v_pk_fma_f32 v[98:99], v[134:135], v[98:99], v[130:131]
	v_pk_mul_f32 v[62:63], v[62:63], v[88:89] op_sel_hi:[1,0]
	v_lshl_add_u64 v[86:87], v[170:171], 0, v[86:87]
	v_pk_mul_f32 v[64:65], v[64:65], v[88:89] op_sel_hi:[1,0]
	v_pk_mul_f32 v[106:107], v[60:61], v[88:89] op_sel_hi:[1,0]
	v_pk_mul_f32 v[88:89], v[58:59], v[88:89] op_sel_hi:[1,0]
	v_cvt_pk_bf16_f32 v58, v102, v103
	v_cvt_pk_bf16_f32 v59, v104, v105
	v_cvt_pk_bf16_f32 v60, v98, v99
	v_cvt_pk_bf16_f32 v61, v100, v101
	v_pk_fma_f32 v[62:63], v[138:139], v[62:63], v[142:143]
	v_pk_fma_f32 v[64:65], v[140:141], v[64:65], v[144:145]
	v_pk_fma_f32 v[98:99], v[136:137], v[106:107], v[132:133]
	v_pk_fma_f32 v[88:89], v[134:135], v[88:89], v[130:131]
	global_store_dwordx4 v[86:87], v[58:61], off
	s_nop 1
	v_cvt_pk_bf16_f32 v58, v62, v63
	v_lshlrev_b64 v[62:63], 12, v[188:189]
	v_cvt_pk_bf16_f32 v59, v64, v65
	v_cvt_pk_bf16_f32 v60, v88, v89
	v_cvt_pk_bf16_f32 v61, v98, v99
	v_lshl_add_u64 v[62:63], v[170:171], 0, v[62:63]
	global_store_dwordx4 v[62:63], v[58:61], off
	ds_read2_b32 v[58:59], v212 offset0:160 offset1:176
	s_waitcnt lgkmcnt(0)
	v_pk_mul_f32 v[38:39], v[38:39], v[58:59] op_sel_hi:[1,0]
	v_pk_mul_f32 v[40:41], v[40:41], v[58:59] op_sel_hi:[1,0]
	v_pk_fma_f32 v[38:39], v[138:139], v[38:39], v[142:143]
	v_pk_mul_f32 v[36:37], v[36:37], v[58:59] op_sel_hi:[1,0]
	v_pk_mul_f32 v[34:35], v[34:35], v[58:59] op_sel_hi:[1,0]
	v_pk_fma_f32 v[40:41], v[140:141], v[40:41], v[144:145]
	v_pk_fma_f32 v[60:61], v[136:137], v[36:37], v[132:133]
	v_pk_fma_f32 v[36:37], v[134:135], v[34:35], v[130:131]
	v_cvt_pk_bf16_f32 v34, v38, v39
	v_lshlrev_b64 v[38:39], 12, v[190:191]
	v_cvt_pk_bf16_f32 v35, v40, v41
	v_cvt_pk_bf16_f32 v36, v36, v37
	v_cvt_pk_bf16_f32 v37, v60, v61
	v_lshl_add_u64 v[60:61], v[170:171], 0, v[38:39]
	global_store_dwordx4 v[60:61], v[34:37], off
	s_nop 1
	v_mov_b32_e32 v34, v59
	v_pk_mul_f32 v[14:15], v[14:15], v[34:35] op_sel_hi:[1,0]
	v_pk_mul_f32 v[16:17], v[16:17], v[34:35] op_sel_hi:[1,0]
	v_pk_fma_f32 v[14:15], v[138:139], v[14:15], v[142:143]
	v_pk_mul_f32 v[12:13], v[12:13], v[34:35] op_sel_hi:[1,0]
	v_pk_mul_f32 v[10:11], v[10:11], v[34:35] op_sel_hi:[1,0]
	v_pk_fma_f32 v[16:17], v[140:141], v[16:17], v[144:145]
	v_pk_fma_f32 v[34:35], v[136:137], v[12:13], v[132:133]
	v_pk_fma_f32 v[12:13], v[134:135], v[10:11], v[130:131]
	v_cvt_pk_bf16_f32 v10, v14, v15
	v_lshlrev_b64 v[14:15], 12, v[192:193]
	v_cvt_pk_bf16_f32 v11, v16, v17
	v_cvt_pk_bf16_f32 v12, v12, v13
	v_cvt_pk_bf16_f32 v13, v34, v35
	v_lshl_add_u64 v[58:59], v[170:171], 0, v[14:15]
	global_store_dwordx4 v[58:59], v[10:13], off
	global_load_dwordx4 v[10:13], v[196:197], off offset:512
	global_load_dwordx4 v[14:17], v[194:195], off offset:512
	global_load_dwordx4 v[34:37], v[194:195], off offset:528
	global_load_dwordx4 v[38:41], v[196:197], off offset:528
	ds_read2_b32 v[64:65], v212 offset1:16
	s_waitcnt lgkmcnt(0)
	v_pk_mul_f32 v[28:29], v[28:29], v[64:65] op_sel_hi:[1,0]
	v_pk_mul_f32 v[26:27], v[26:27], v[64:65] op_sel_hi:[1,0]
	v_pk_mul_f32 v[32:33], v[32:33], v[64:65] op_sel_hi:[1,0]
	v_pk_mul_f32 v[30:31], v[30:31], v[64:65] op_sel_hi:[1,0]
	v_mov_b32_e32 v64, v65
	v_pk_mul_f32 v[44:45], v[44:45], v[64:65] op_sel_hi:[1,0]
	v_pk_mul_f32 v[42:43], v[42:43], v[64:65] op_sel_hi:[1,0]
	v_pk_mul_f32 v[52:53], v[52:53], v[64:65] op_sel_hi:[1,0]
	v_pk_mul_f32 v[50:51], v[50:51], v[64:65] op_sel_hi:[1,0]
	s_waitcnt vmcnt(2)
	v_pk_fma_f32 v[28:29], v[16:17], v[28:29], v[12:13]
	v_pk_fma_f32 v[26:27], v[14:15], v[26:27], v[10:11]
	s_waitcnt vmcnt(0)
	v_pk_fma_f32 v[32:33], v[36:37], v[32:33], v[40:41]
	v_pk_fma_f32 v[30:31], v[34:35], v[30:31], v[38:39]
	v_pk_fma_f32 v[44:45], v[16:17], v[44:45], v[12:13]
	v_pk_fma_f32 v[42:43], v[14:15], v[42:43], v[10:11]
	v_pk_fma_f32 v[52:53], v[36:37], v[52:53], v[40:41]
	v_pk_fma_f32 v[50:51], v[34:35], v[50:51], v[38:39]
	v_cvt_pk_bf16_f32 v26, v26, v27
	v_cvt_pk_bf16_f32 v27, v28, v29
	v_cvt_pk_bf16_f32 v28, v30, v31
	v_cvt_pk_bf16_f32 v29, v32, v33
	v_cvt_pk_bf16_f32 v30, v42, v43
	v_cvt_pk_bf16_f32 v31, v44, v45
	v_cvt_pk_bf16_f32 v32, v50, v51
	v_cvt_pk_bf16_f32 v33, v52, v53
	global_store_dwordx4 v[180:181], v[26:29], off offset:256
	global_store_dwordx4 v[178:179], v[30:33], off offset:256
	ds_read2_b32 v[26:27], v212 offset0:32 offset1:48
	s_waitcnt lgkmcnt(0)
	v_pk_mul_f32 v[28:29], v[68:69], v[26:27] op_sel_hi:[1,0]
	v_pk_mul_f32 v[30:31], v[66:67], v[26:27] op_sel_hi:[1,0]
	v_pk_mul_f32 v[32:33], v[72:73], v[26:27] op_sel_hi:[1,0]
	v_pk_mul_f32 v[42:43], v[70:71], v[26:27] op_sel_hi:[1,0]
	v_mov_b32_e32 v26, v27
	v_pk_fma_f32 v[28:29], v[16:17], v[28:29], v[12:13]
	v_pk_fma_f32 v[30:31], v[14:15], v[30:31], v[10:11]
	v_pk_fma_f32 v[32:33], v[36:37], v[32:33], v[40:41]
	v_pk_fma_f32 v[42:43], v[34:35], v[42:43], v[38:39]
	v_pk_mul_f32 v[44:45], v[92:93], v[26:27] op_sel_hi:[1,0]
	v_pk_mul_f32 v[50:51], v[90:91], v[26:27] op_sel_hi:[1,0]
	v_pk_mul_f32 v[52:53], v[96:97], v[26:27] op_sel_hi:[1,0]
	v_pk_mul_f32 v[64:65], v[94:95], v[26:27] op_sel_hi:[1,0]
	v_cvt_pk_bf16_f32 v26, v30, v31
	v_cvt_pk_bf16_f32 v27, v28, v29
	v_cvt_pk_bf16_f32 v28, v42, v43
	v_cvt_pk_bf16_f32 v29, v32, v33
	v_pk_fma_f32 v[30:31], v[16:17], v[44:45], v[12:13]
	v_pk_fma_f32 v[32:33], v[14:15], v[50:51], v[10:11]
	v_pk_fma_f32 v[42:43], v[36:37], v[52:53], v[40:41]
	v_pk_fma_f32 v[44:45], v[34:35], v[64:65], v[38:39]
	global_store_dwordx4 v[84:85], v[26:29], off offset:256
	s_nop 1
	v_cvt_pk_bf16_f32 v26, v32, v33
	v_cvt_pk_bf16_f32 v27, v30, v31
	v_cvt_pk_bf16_f32 v28, v44, v45
	v_cvt_pk_bf16_f32 v29, v42, v43
	global_store_dwordx4 v[82:83], v[26:29], off offset:256
	ds_read2_b32 v[26:27], v212 offset0:128 offset1:144
	s_waitcnt lgkmcnt(0)
	v_pk_mul_f32 v[30:31], v[78:79], v[26:27] op_sel_hi:[1,0]
	v_pk_mul_f32 v[28:29], v[80:81], v[26:27] op_sel_hi:[1,0]
	v_pk_mul_f32 v[32:33], v[76:77], v[26:27] op_sel_hi:[1,0]
	v_pk_mul_f32 v[42:43], v[74:75], v[26:27] op_sel_hi:[1,0]
	v_mov_b32_e32 v44, v27
	v_pk_fma_f32 v[28:29], v[16:17], v[28:29], v[12:13]
	v_pk_fma_f32 v[26:27], v[14:15], v[30:31], v[10:11]
	v_pk_fma_f32 v[30:31], v[36:37], v[32:33], v[40:41]
	v_pk_fma_f32 v[32:33], v[34:35], v[42:43], v[38:39]
	v_pk_mul_f32 v[42:43], v[56:57], v[44:45] op_sel_hi:[1,0]
	v_pk_mul_f32 v[50:51], v[54:55], v[44:45] op_sel_hi:[1,0]
	v_cvt_pk_bf16_f32 v26, v26, v27
	v_cvt_pk_bf16_f32 v27, v28, v29
	v_cvt_pk_bf16_f32 v28, v32, v33
	v_cvt_pk_bf16_f32 v29, v30, v31
	v_pk_mul_f32 v[30:31], v[48:49], v[44:45] op_sel_hi:[1,0]
	v_pk_mul_f32 v[32:33], v[46:47], v[44:45] op_sel_hi:[1,0]
	global_store_dwordx4 v[86:87], v[26:29], off offset:256
	v_pk_fma_f32 v[30:31], v[36:37], v[30:31], v[40:41]
	v_pk_fma_f32 v[32:33], v[34:35], v[32:33], v[38:39]
	v_pk_fma_f32 v[28:29], v[16:17], v[42:43], v[12:13]
	v_pk_fma_f32 v[26:27], v[14:15], v[50:51], v[10:11]
	s_nop 0
	v_cvt_pk_bf16_f32 v26, v26, v27
	v_cvt_pk_bf16_f32 v27, v28, v29
	v_cvt_pk_bf16_f32 v28, v32, v33
	v_cvt_pk_bf16_f32 v29, v30, v31
	global_store_dwordx4 v[62:63], v[26:29], off offset:256
	ds_read2_b32 v[26:27], v212 offset0:160 offset1:176
	s_waitcnt lgkmcnt(0)
	v_pk_mul_f32 v[24:25], v[24:25], v[26:27] op_sel_hi:[1,0]
	v_pk_mul_f32 v[22:23], v[22:23], v[26:27] op_sel_hi:[1,0]
	v_pk_mul_f32 v[20:21], v[20:21], v[26:27] op_sel_hi:[1,0]
	v_pk_mul_f32 v[18:19], v[18:19], v[26:27] op_sel_hi:[1,0]
	v_pk_fma_f32 v[24:25], v[16:17], v[24:25], v[12:13]
	v_pk_fma_f32 v[22:23], v[14:15], v[22:23], v[10:11]
	v_pk_fma_f32 v[28:29], v[36:37], v[20:21], v[40:41]
	v_pk_fma_f32 v[20:21], v[34:35], v[18:19], v[38:39]
	v_cvt_pk_bf16_f32 v18, v22, v23
	v_cvt_pk_bf16_f32 v19, v24, v25
	v_cvt_pk_bf16_f32 v20, v20, v21
	v_cvt_pk_bf16_f32 v21, v28, v29
	global_store_dwordx4 v[60:61], v[18:21], off offset:256
	s_nop 1
	v_mov_b32_e32 v18, v27
	v_pk_mul_f32 v[8:9], v[8:9], v[18:19] op_sel_hi:[1,0]
	v_pk_mul_f32 v[6:7], v[6:7], v[18:19] op_sel_hi:[1,0]
	v_pk_mul_f32 v[4:5], v[4:5], v[18:19] op_sel_hi:[1,0]
	v_pk_mul_f32 v[2:3], v[2:3], v[18:19] op_sel_hi:[1,0]
	v_pk_fma_f32 v[8:9], v[16:17], v[8:9], v[12:13]
	v_pk_fma_f32 v[6:7], v[14:15], v[6:7], v[10:11]
	v_pk_fma_f32 v[10:11], v[36:37], v[4:5], v[40:41]
	v_pk_fma_f32 v[4:5], v[34:35], v[2:3], v[38:39]
	v_cvt_pk_bf16_f32 v2, v6, v7
	v_cvt_pk_bf16_f32 v3, v8, v9
	v_cvt_pk_bf16_f32 v4, v4, v5
	v_cvt_pk_bf16_f32 v5, v10, v11
	global_store_dwordx4 v[58:59], v[2:5], off offset:256
	s_cbranch_vccnz .LBB0_352
	s_andn2_b64 vcc, exec, s[12:13]
	s_cbranch_vccnz .LBB0_351
	s_barrier
	s_branch .LBB0_351

.LBB0_723:
	s_waitcnt lgkmcnt(0)
	s_cmp_gt_u32 s3, 63
	s_cbranch_scc1 .LBB0_736
	s_memrealtime s[42:43]
	s_lshl_b32 s14, s36, 6
	s_ashr_i32 s15, s14, 31
	s_lshl_b64 s[14:15], s[14:15], 2
	s_add_u32 s44, s61, s14
	s_addc_u32 s45, s62, s15
	s_mov_b32 s3, 1
	s_branch .LBB0_726

.LBB0_738:
	s_ashr_i32 s39, s38, 31
	s_lshl_b64 s[16:17], s[38:39], 13
	s_mul_hi_i32 s15, s38, 0x12000
	s_mul_i32 s14, s38, 0x12000
	s_waitcnt vmcnt(0) lgkmcnt(0)
	s_barrier
	v_lshl_add_u64 v[130:131], v[164:165], 0, v[186:187]
	global_store_dwordx4 v[130:131], v[82:85], off nt
	global_store_dwordx4 v[130:131], v[78:81], off offset:16 nt
	global_store_dwordx4 v[130:131], v[22:25], off offset:512 nt
	global_store_dwordx4 v[130:131], v[26:29], off offset:528 nt
	v_lshl_add_u64 v[130:131], v[164:165], 0, v[192:193]
	global_store_dwordx4 v[130:131], v[110:113], off nt
	global_store_dwordx4 v[130:131], v[106:109], off offset:16 nt
	global_store_dwordx4 v[130:131], v[42:45], off offset:512 nt
	global_store_dwordx4 v[130:131], v[46:49], off offset:528 nt
	v_lshl_add_u64 v[130:131], v[164:165], 0, v[196:197]
	global_store_dwordx4 v[130:131], v[118:121], off nt
	global_store_dwordx4 v[130:131], v[114:117], off offset:16 nt
	global_store_dwordx4 v[130:131], v[62:65], off offset:512 nt
	global_store_dwordx4 v[130:131], v[70:73], off offset:528 nt
	v_lshl_add_u64 v[130:131], v[164:165], 0, v[200:201]
	global_store_dwordx4 v[130:131], v[126:129], off nt
	global_store_dwordx4 v[130:131], v[122:125], off offset:16 nt
	global_store_dwordx4 v[130:131], v[90:93], off offset:512 nt
	global_store_dwordx4 v[130:131], v[94:97], off offset:528 nt
	v_lshl_add_u64 v[130:131], v[164:165], 0, v[202:203]
	global_store_dwordx4 v[130:131], v[102:105], off nt
	global_store_dwordx4 v[130:131], v[98:101], off offset:16 nt
	global_store_dwordx4 v[130:131], v[86:89], off offset:512 nt
	global_store_dwordx4 v[130:131], v[74:77], off offset:528 nt
	v_lshl_add_u64 v[130:131], v[164:165], 0, v[204:205]
	global_store_dwordx4 v[130:131], v[66:69], off nt
	global_store_dwordx4 v[130:131], v[58:61], off offset:16 nt
	global_store_dwordx4 v[130:131], v[54:57], off offset:512 nt
	global_store_dwordx4 v[130:131], v[50:53], off offset:528 nt
	v_lshl_add_u64 v[130:131], v[164:165], 0, v[206:207]
	global_store_dwordx4 v[130:131], v[38:41], off nt
	global_store_dwordx4 v[130:131], v[34:37], off offset:16 nt
	global_store_dwordx4 v[130:131], v[30:33], off offset:512 nt
	global_store_dwordx4 v[130:131], v[18:21], off offset:528 nt
	v_lshl_add_u64 v[130:131], v[164:165], 0, v[208:209]
	global_store_dwordx4 v[130:131], v[14:17], off nt
	global_store_dwordx4 v[130:131], v[10:13], off offset:16 nt
	global_store_dwordx4 v[130:131], v[6:9], off offset:512 nt
	global_store_dwordx4 v[130:131], v[2:5], off offset:528 nt
	v_lshl_add_u64 v[186:187], v[166:167], 0, s[16:17]
	v_lshl_add_u64 v[192:193], v[168:169], 0, s[14:15]
	global_load_dwordx4 v[138:141], v[186:187], off
	global_load_dwordx4 v[142:145], v[192:193], off
	global_load_dwordx4 v[130:133], v[192:193], off offset:16
	global_load_dwordx4 v[134:137], v[186:187], off offset:16
	ds_read2_b32 v[196:197], v213 offset1:16
	v_lshlrev_b64 v[178:179], 12, v[178:179]
	v_lshlrev_b64 v[200:201], 12, v[180:181]
	v_lshl_add_u64 v[180:181], v[170:171], 0, v[178:179]
	v_lshl_add_u64 v[178:179], v[170:171], 0, v[200:201]
	s_waitcnt lgkmcnt(0)
	v_pk_mul_f32 v[84:85], v[84:85], v[196:197] op_sel_hi:[1,0]
	v_pk_mul_f32 v[82:83], v[82:83], v[196:197] op_sel_hi:[1,0]
	v_pk_mul_f32 v[80:81], v[80:81], v[196:197] op_sel_hi:[1,0]
	v_pk_mul_f32 v[78:79], v[78:79], v[196:197] op_sel_hi:[1,0]
	v_mov_b32_e32 v196, v197
	v_pk_mul_f32 v[112:113], v[112:113], v[196:197] op_sel_hi:[1,0]
	v_pk_mul_f32 v[110:111], v[110:111], v[196:197] op_sel_hi:[1,0]
	v_pk_mul_f32 v[108:109], v[108:109], v[196:197] op_sel_hi:[1,0]
	v_pk_mul_f32 v[106:107], v[106:107], v[196:197] op_sel_hi:[1,0]
	s_andn2_b64 vcc, exec, s[34:35]
	s_mov_b64 s[34:35], -1
	s_waitcnt vmcnt(2)
	v_pk_fma_f32 v[84:85], v[140:141], v[84:85], v[144:145]
	v_pk_fma_f32 v[82:83], v[138:139], v[82:83], v[142:143]
	s_waitcnt vmcnt(0)
	v_pk_fma_f32 v[196:197], v[136:137], v[80:81], v[132:133]
	v_pk_fma_f32 v[80:81], v[134:135], v[78:79], v[130:131]
	v_pk_fma_f32 v[112:113], v[140:141], v[112:113], v[144:145]
	v_pk_fma_f32 v[110:111], v[138:139], v[110:111], v[142:143]
	v_pk_fma_f32 v[108:109], v[136:137], v[108:109], v[132:133]
	v_pk_fma_f32 v[106:107], v[134:135], v[106:107], v[130:131]
	v_cvt_pk_bf16_f32 v78, v82, v83
	v_cvt_pk_bf16_f32 v79, v84, v85
	v_cvt_pk_bf16_f32 v80, v80, v81
	v_cvt_pk_bf16_f32 v81, v196, v197
	v_cvt_pk_bf16_f32 v82, v110, v111
	v_cvt_pk_bf16_f32 v83, v112, v113
	v_cvt_pk_bf16_f32 v84, v106, v107
	v_cvt_pk_bf16_f32 v85, v108, v109
	global_store_dwordx4 v[180:181], v[78:81], off
	global_store_dwordx4 v[178:179], v[82:85], off
	ds_read2_b32 v[82:83], v213 offset0:32 offset1:48
	v_lshlrev_b64 v[78:79], 12, v[182:183]
	v_lshlrev_b64 v[84:85], 12, v[184:185]
	v_lshl_add_u64 v[80:81], v[170:171], 0, v[78:79]
	v_lshl_add_u64 v[78:79], v[170:171], 0, v[84:85]
	s_waitcnt lgkmcnt(0)
	v_pk_mul_f32 v[84:85], v[120:121], v[82:83] op_sel_hi:[1,0]
	v_pk_mul_f32 v[106:107], v[118:119], v[82:83] op_sel_hi:[1,0]
	v_pk_mul_f32 v[108:109], v[116:117], v[82:83] op_sel_hi:[1,0]
	v_pk_mul_f32 v[110:111], v[114:115], v[82:83] op_sel_hi:[1,0]
	v_mov_b32_e32 v82, v83
	v_pk_fma_f32 v[84:85], v[140:141], v[84:85], v[144:145]
	v_pk_fma_f32 v[106:107], v[138:139], v[106:107], v[142:143]
	v_pk_fma_f32 v[108:109], v[136:137], v[108:109], v[132:133]
	v_pk_fma_f32 v[110:111], v[134:135], v[110:111], v[130:131]
	v_pk_mul_f32 v[112:113], v[128:129], v[82:83] op_sel_hi:[1,0]
	v_pk_mul_f32 v[114:115], v[126:127], v[82:83] op_sel_hi:[1,0]
	v_pk_mul_f32 v[116:117], v[124:125], v[82:83] op_sel_hi:[1,0]
	v_pk_mul_f32 v[118:119], v[122:123], v[82:83] op_sel_hi:[1,0]
	v_cvt_pk_bf16_f32 v82, v106, v107
	v_cvt_pk_bf16_f32 v83, v84, v85
	v_cvt_pk_bf16_f32 v84, v110, v111
	v_cvt_pk_bf16_f32 v85, v108, v109
	v_pk_fma_f32 v[106:107], v[140:141], v[112:113], v[144:145]
	v_pk_fma_f32 v[108:109], v[138:139], v[114:115], v[142:143]
	v_pk_fma_f32 v[110:111], v[136:137], v[116:117], v[132:133]
	v_pk_fma_f32 v[112:113], v[134:135], v[118:119], v[130:131]
	global_store_dwordx4 v[80:81], v[82:85], off
	s_nop 1
	v_cvt_pk_bf16_f32 v82, v108, v109
	v_cvt_pk_bf16_f32 v83, v106, v107
	v_cvt_pk_bf16_f32 v84, v112, v113
	v_cvt_pk_bf16_f32 v85, v110, v111
	global_store_dwordx4 v[78:79], v[82:85], off
	ds_read2_b32 v[84:85], v213 offset0:128 offset1:144
	s_waitcnt lgkmcnt(0)
	v_pk_mul_f32 v[104:105], v[104:105], v[84:85] op_sel_hi:[1,0]
	v_pk_mul_f32 v[102:103], v[102:103], v[84:85] op_sel_hi:[1,0]
	v_pk_mul_f32 v[100:101], v[100:101], v[84:85] op_sel_hi:[1,0]
	v_pk_mul_f32 v[98:99], v[98:99], v[84:85] op_sel_hi:[1,0]
	v_mov_b32_e32 v84, v85
	v_lshlrev_b64 v[82:83], 12, v[188:189]
	v_pk_fma_f32 v[104:105], v[140:141], v[104:105], v[144:145]
	v_pk_fma_f32 v[102:103], v[138:139], v[102:103], v[142:143]
	v_pk_fma_f32 v[100:101], v[136:137], v[100:101], v[132:133]
	v_pk_fma_f32 v[98:99], v[134:135], v[98:99], v[130:131]
	v_pk_mul_f32 v[66:67], v[66:67], v[84:85] op_sel_hi:[1,0]
	v_lshl_add_u64 v[82:83], v[170:171], 0, v[82:83]
	v_pk_mul_f32 v[68:69], v[68:69], v[84:85] op_sel_hi:[1,0]
	v_pk_mul_f32 v[106:107], v[60:61], v[84:85] op_sel_hi:[1,0]
	v_pk_mul_f32 v[84:85], v[58:59], v[84:85] op_sel_hi:[1,0]
	v_cvt_pk_bf16_f32 v58, v102, v103
	v_cvt_pk_bf16_f32 v59, v104, v105
	v_cvt_pk_bf16_f32 v60, v98, v99
	v_cvt_pk_bf16_f32 v61, v100, v101
	v_pk_fma_f32 v[66:67], v[138:139], v[66:67], v[142:143]
	v_pk_fma_f32 v[68:69], v[140:141], v[68:69], v[144:145]
	v_pk_fma_f32 v[98:99], v[136:137], v[106:107], v[132:133]
	v_pk_fma_f32 v[84:85], v[134:135], v[84:85], v[130:131]
	global_store_dwordx4 v[82:83], v[58:61], off
	s_nop 1
	v_cvt_pk_bf16_f32 v58, v66, v67
	v_lshlrev_b64 v[66:67], 12, v[190:191]
	v_cvt_pk_bf16_f32 v59, v68, v69
	v_cvt_pk_bf16_f32 v60, v84, v85
	v_cvt_pk_bf16_f32 v61, v98, v99
	v_lshl_add_u64 v[66:67], v[170:171], 0, v[66:67]
	global_store_dwordx4 v[66:67], v[58:61], off
	ds_read2_b32 v[58:59], v213 offset0:160 offset1:176
	s_waitcnt lgkmcnt(0)
	v_pk_mul_f32 v[38:39], v[38:39], v[58:59] op_sel_hi:[1,0]
	v_pk_mul_f32 v[40:41], v[40:41], v[58:59] op_sel_hi:[1,0]
	v_pk_fma_f32 v[38:39], v[138:139], v[38:39], v[142:143]
	v_pk_mul_f32 v[36:37], v[36:37], v[58:59] op_sel_hi:[1,0]
	v_pk_mul_f32 v[34:35], v[34:35], v[58:59] op_sel_hi:[1,0]
	v_pk_fma_f32 v[40:41], v[140:141], v[40:41], v[144:145]
	v_pk_fma_f32 v[60:61], v[136:137], v[36:37], v[132:133]
	v_pk_fma_f32 v[36:37], v[134:135], v[34:35], v[130:131]
	v_cvt_pk_bf16_f32 v34, v38, v39
	v_lshlrev_b64 v[38:39], 12, v[194:195]
	v_cvt_pk_bf16_f32 v35, v40, v41
	v_cvt_pk_bf16_f32 v36, v36, v37
	v_cvt_pk_bf16_f32 v37, v60, v61
	v_lshl_add_u64 v[60:61], v[170:171], 0, v[38:39]
	global_store_dwordx4 v[60:61], v[34:37], off
	s_nop 1
	v_mov_b32_e32 v34, v59
	v_pk_mul_f32 v[14:15], v[14:15], v[34:35] op_sel_hi:[1,0]
	v_pk_mul_f32 v[16:17], v[16:17], v[34:35] op_sel_hi:[1,0]
	v_pk_fma_f32 v[14:15], v[138:139], v[14:15], v[142:143]
	v_pk_mul_f32 v[12:13], v[12:13], v[34:35] op_sel_hi:[1,0]
	v_pk_mul_f32 v[10:11], v[10:11], v[34:35] op_sel_hi:[1,0]
	v_pk_fma_f32 v[16:17], v[140:141], v[16:17], v[144:145]
	v_pk_fma_f32 v[34:35], v[136:137], v[12:13], v[132:133]
	v_pk_fma_f32 v[12:13], v[134:135], v[10:11], v[130:131]
	v_cvt_pk_bf16_f32 v10, v14, v15
	v_lshlrev_b64 v[14:15], 12, v[198:199]
	v_cvt_pk_bf16_f32 v11, v16, v17
	v_cvt_pk_bf16_f32 v12, v12, v13
	v_cvt_pk_bf16_f32 v13, v34, v35
	v_lshl_add_u64 v[58:59], v[170:171], 0, v[14:15]
	global_store_dwordx4 v[58:59], v[10:13], off
	global_load_dwordx4 v[10:13], v[192:193], off offset:512
	global_load_dwordx4 v[14:17], v[186:187], off offset:512
	global_load_dwordx4 v[34:37], v[186:187], off offset:528
	global_load_dwordx4 v[38:41], v[192:193], off offset:528
	ds_read2_b32 v[68:69], v213 offset1:16
	s_waitcnt lgkmcnt(0)
	v_pk_mul_f32 v[24:25], v[24:25], v[68:69] op_sel_hi:[1,0]
	v_pk_mul_f32 v[22:23], v[22:23], v[68:69] op_sel_hi:[1,0]
	v_pk_mul_f32 v[28:29], v[28:29], v[68:69] op_sel_hi:[1,0]
	v_pk_mul_f32 v[26:27], v[26:27], v[68:69] op_sel_hi:[1,0]
	v_mov_b32_e32 v68, v69
	v_pk_mul_f32 v[44:45], v[44:45], v[68:69] op_sel_hi:[1,0]
	v_pk_mul_f32 v[42:43], v[42:43], v[68:69] op_sel_hi:[1,0]
	v_pk_mul_f32 v[48:49], v[48:49], v[68:69] op_sel_hi:[1,0]
	v_pk_mul_f32 v[46:47], v[46:47], v[68:69] op_sel_hi:[1,0]
	s_waitcnt vmcnt(2)
	v_pk_fma_f32 v[24:25], v[16:17], v[24:25], v[12:13]
	v_pk_fma_f32 v[22:23], v[14:15], v[22:23], v[10:11]
	s_waitcnt vmcnt(0)
	v_pk_fma_f32 v[28:29], v[36:37], v[28:29], v[40:41]
	v_pk_fma_f32 v[26:27], v[34:35], v[26:27], v[38:39]
	v_pk_fma_f32 v[44:45], v[16:17], v[44:45], v[12:13]
	v_pk_fma_f32 v[42:43], v[14:15], v[42:43], v[10:11]
	v_pk_fma_f32 v[48:49], v[36:37], v[48:49], v[40:41]
	v_pk_fma_f32 v[46:47], v[34:35], v[46:47], v[38:39]
	v_cvt_pk_bf16_f32 v22, v22, v23
	v_cvt_pk_bf16_f32 v23, v24, v25
	v_cvt_pk_bf16_f32 v24, v26, v27
	v_cvt_pk_bf16_f32 v25, v28, v29
	v_cvt_pk_bf16_f32 v26, v42, v43
	v_cvt_pk_bf16_f32 v27, v44, v45
	v_cvt_pk_bf16_f32 v28, v46, v47
	v_cvt_pk_bf16_f32 v29, v48, v49
	global_store_dwordx4 v[180:181], v[22:25], off offset:256
	global_store_dwordx4 v[178:179], v[26:29], off offset:256
	ds_read2_b32 v[22:23], v213 offset0:32 offset1:48
	s_waitcnt lgkmcnt(0)
	v_pk_mul_f32 v[24:25], v[64:65], v[22:23] op_sel_hi:[1,0]
	v_pk_mul_f32 v[26:27], v[62:63], v[22:23] op_sel_hi:[1,0]
	v_pk_mul_f32 v[28:29], v[72:73], v[22:23] op_sel_hi:[1,0]
	v_pk_mul_f32 v[42:43], v[70:71], v[22:23] op_sel_hi:[1,0]
	v_mov_b32_e32 v22, v23
	v_pk_fma_f32 v[24:25], v[16:17], v[24:25], v[12:13]
	v_pk_fma_f32 v[26:27], v[14:15], v[26:27], v[10:11]
	v_pk_fma_f32 v[28:29], v[36:37], v[28:29], v[40:41]
	v_pk_fma_f32 v[42:43], v[34:35], v[42:43], v[38:39]
	v_pk_mul_f32 v[44:45], v[92:93], v[22:23] op_sel_hi:[1,0]
	v_pk_mul_f32 v[46:47], v[90:91], v[22:23] op_sel_hi:[1,0]
	v_pk_mul_f32 v[48:49], v[96:97], v[22:23] op_sel_hi:[1,0]
	v_pk_mul_f32 v[62:63], v[94:95], v[22:23] op_sel_hi:[1,0]
	v_cvt_pk_bf16_f32 v22, v26, v27
	v_cvt_pk_bf16_f32 v23, v24, v25
	v_cvt_pk_bf16_f32 v24, v42, v43
	v_cvt_pk_bf16_f32 v25, v28, v29
	v_pk_fma_f32 v[26:27], v[16:17], v[44:45], v[12:13]
	v_pk_fma_f32 v[28:29], v[14:15], v[46:47], v[10:11]
	v_pk_fma_f32 v[42:43], v[36:37], v[48:49], v[40:41]
	v_pk_fma_f32 v[44:45], v[34:35], v[62:63], v[38:39]
	global_store_dwordx4 v[80:81], v[22:25], off offset:256
	s_nop 1
	v_cvt_pk_bf16_f32 v22, v28, v29
	v_cvt_pk_bf16_f32 v23, v26, v27
	v_cvt_pk_bf16_f32 v24, v44, v45
	v_cvt_pk_bf16_f32 v25, v42, v43
	global_store_dwordx4 v[78:79], v[22:25], off offset:256
	ds_read2_b32 v[22:23], v213 offset0:128 offset1:144
	s_waitcnt lgkmcnt(0)
	v_pk_mul_f32 v[26:27], v[86:87], v[22:23] op_sel_hi:[1,0]
	v_pk_mul_f32 v[24:25], v[88:89], v[22:23] op_sel_hi:[1,0]
	v_pk_mul_f32 v[28:29], v[76:77], v[22:23] op_sel_hi:[1,0]
	v_pk_mul_f32 v[42:43], v[74:75], v[22:23] op_sel_hi:[1,0]
	v_mov_b32_e32 v44, v23
	v_pk_fma_f32 v[24:25], v[16:17], v[24:25], v[12:13]
	v_pk_fma_f32 v[22:23], v[14:15], v[26:27], v[10:11]
	v_pk_fma_f32 v[26:27], v[36:37], v[28:29], v[40:41]
	v_pk_fma_f32 v[28:29], v[34:35], v[42:43], v[38:39]
	v_pk_mul_f32 v[42:43], v[56:57], v[44:45] op_sel_hi:[1,0]
	v_pk_mul_f32 v[46:47], v[54:55], v[44:45] op_sel_hi:[1,0]
	v_cvt_pk_bf16_f32 v22, v22, v23
	v_cvt_pk_bf16_f32 v23, v24, v25
	v_cvt_pk_bf16_f32 v24, v28, v29
	v_cvt_pk_bf16_f32 v25, v26, v27
	v_pk_mul_f32 v[26:27], v[52:53], v[44:45] op_sel_hi:[1,0]
	v_pk_mul_f32 v[28:29], v[50:51], v[44:45] op_sel_hi:[1,0]
	global_store_dwordx4 v[82:83], v[22:25], off offset:256
	v_pk_fma_f32 v[26:27], v[36:37], v[26:27], v[40:41]
	v_pk_fma_f32 v[28:29], v[34:35], v[28:29], v[38:39]
	v_pk_fma_f32 v[24:25], v[16:17], v[42:43], v[12:13]
	v_pk_fma_f32 v[22:23], v[14:15], v[46:47], v[10:11]
	s_nop 0
	v_cvt_pk_bf16_f32 v22, v22, v23
	v_cvt_pk_bf16_f32 v23, v24, v25
	v_cvt_pk_bf16_f32 v24, v28, v29
	v_cvt_pk_bf16_f32 v25, v26, v27
	global_store_dwordx4 v[66:67], v[22:25], off offset:256
	ds_read2_b32 v[22:23], v213 offset0:160 offset1:176
	s_waitcnt lgkmcnt(0)
	v_pk_mul_f32 v[26:27], v[30:31], v[22:23] op_sel_hi:[1,0]
	v_pk_mul_f32 v[24:25], v[32:33], v[22:23] op_sel_hi:[1,0]
	v_pk_mul_f32 v[20:21], v[20:21], v[22:23] op_sel_hi:[1,0]
	v_pk_mul_f32 v[18:19], v[18:19], v[22:23] op_sel_hi:[1,0]
	v_pk_fma_f32 v[24:25], v[16:17], v[24:25], v[12:13]
	v_pk_fma_f32 v[26:27], v[14:15], v[26:27], v[10:11]
	v_pk_fma_f32 v[28:29], v[36:37], v[20:21], v[40:41]
	v_pk_fma_f32 v[20:21], v[34:35], v[18:19], v[38:39]
	v_cvt_pk_bf16_f32 v18, v26, v27
	v_cvt_pk_bf16_f32 v19, v24, v25
	v_cvt_pk_bf16_f32 v20, v20, v21
	v_cvt_pk_bf16_f32 v21, v28, v29
	global_store_dwordx4 v[60:61], v[18:21], off offset:256
	s_nop 1
	v_mov_b32_e32 v18, v23
	v_pk_mul_f32 v[8:9], v[8:9], v[18:19] op_sel_hi:[1,0]
	v_pk_mul_f32 v[6:7], v[6:7], v[18:19] op_sel_hi:[1,0]
	v_pk_mul_f32 v[4:5], v[4:5], v[18:19] op_sel_hi:[1,0]
	v_pk_mul_f32 v[2:3], v[2:3], v[18:19] op_sel_hi:[1,0]
	v_pk_fma_f32 v[8:9], v[16:17], v[8:9], v[12:13]
	v_pk_fma_f32 v[6:7], v[14:15], v[6:7], v[10:11]
	v_pk_fma_f32 v[10:11], v[36:37], v[4:5], v[40:41]
	v_pk_fma_f32 v[4:5], v[34:35], v[2:3], v[38:39]
	v_cvt_pk_bf16_f32 v2, v6, v7
	v_cvt_pk_bf16_f32 v3, v8, v9
	v_cvt_pk_bf16_f32 v4, v4, v5
	v_cvt_pk_bf16_f32 v5, v10, v11
	global_store_dwordx4 v[58:59], v[2:5], off offset:256
	s_cbranch_vccnz .LBB0_697
	s_andn2_b64 vcc, exec, s[24:25]
	s_cbranch_vccnz .LBB0_696
	s_barrier
	s_branch .LBB0_696

.LBB0_901:
	s_cmp_gt_u32 s3, 63
	s_cbranch_scc1 .LBB0_914
	s_memrealtime s[40:41]
	s_lshl_b32 s14, s34, 6
	s_ashr_i32 s15, s14, 31
	s_lshl_b64 s[14:15], s[14:15], 2
	s_add_u32 s42, s66, s14
	s_addc_u32 s43, s67, s15
	s_mov_b32 s3, 1
	s_branch .LBB0_904

.LBB0_916:
	s_lshl_b64 s[34:35], s[36:37], 13
	s_waitcnt vmcnt(0) lgkmcnt(0)
	s_barrier
	v_lshlrev_b64 v[130:131], 13, v[184:185]
	v_lshlrev_b64 v[132:133], 13, v[186:187]
	v_lshlrev_b64 v[134:135], 13, v[188:189]
	v_lshl_add_u64 v[130:131], v[164:165], 0, v[130:131]
	global_store_dwordx4 v[130:131], v[30:33], off nt
	global_store_dwordx4 v[130:131], v[26:29], off offset:16 nt
	global_store_dwordx4 v[130:131], v[2:5], off offset:512 nt
	global_store_dwordx4 v[130:131], v[6:9], off offset:528 nt
	v_lshl_add_u64 v[130:131], v[164:165], 0, v[132:133]
	global_store_dwordx4 v[130:131], v[46:49], off nt
	global_store_dwordx4 v[130:131], v[42:45], off offset:16 nt
	global_store_dwordx4 v[130:131], v[10:13], off offset:512 nt
	global_store_dwordx4 v[130:131], v[14:17], off offset:528 nt
	v_lshl_add_u64 v[130:131], v[164:165], 0, v[134:135]
	global_store_dwordx4 v[130:131], v[62:65], off nt
	global_store_dwordx4 v[130:131], v[58:61], off offset:16 nt
	global_store_dwordx4 v[130:131], v[18:21], off offset:512 nt
	global_store_dwordx4 v[130:131], v[22:25], off offset:528 nt
	v_lshl_add_u64 v[130:131], v[164:165], 0, v[206:207]
	global_store_dwordx4 v[130:131], v[94:97], off nt
	global_store_dwordx4 v[130:131], v[90:93], off offset:16 nt
	global_store_dwordx4 v[130:131], v[34:37], off offset:512 nt
	global_store_dwordx4 v[130:131], v[38:41], off offset:528 nt
	v_lshl_add_u64 v[130:131], v[164:165], 0, v[208:209]
	global_store_dwordx4 v[130:131], v[114:117], off nt
	global_store_dwordx4 v[130:131], v[110:113], off offset:16 nt
	global_store_dwordx4 v[130:131], v[50:53], off offset:512 nt
	global_store_dwordx4 v[130:131], v[54:57], off offset:528 nt
	v_lshl_add_u64 v[130:131], v[164:165], 0, v[210:211]
	global_store_dwordx4 v[130:131], v[126:129], off nt
	global_store_dwordx4 v[130:131], v[122:125], off offset:16 nt
	global_store_dwordx4 v[130:131], v[82:85], off offset:512 nt
	global_store_dwordx4 v[130:131], v[86:89], off offset:528 nt
	v_lshl_add_u64 v[130:131], v[164:165], 0, v[212:213]
	global_store_dwordx4 v[130:131], v[118:121], off nt
	global_store_dwordx4 v[130:131], v[106:109], off offset:16 nt
	global_store_dwordx4 v[130:131], v[102:105], off offset:512 nt
	global_store_dwordx4 v[130:131], v[98:101], off offset:528 nt
	v_lshl_add_u64 v[130:131], v[164:165], 0, v[214:215]
	global_store_dwordx4 v[130:131], v[78:81], off nt
	global_store_dwordx4 v[130:131], v[74:77], off offset:16 nt
	global_store_dwordx4 v[130:131], v[70:73], off offset:512 nt
	global_store_dwordx4 v[130:131], v[66:69], off offset:528 nt
	v_lshl_add_u64 v[202:203], v[166:167], 0, s[34:35]
	v_lshl_add_u64 v[204:205], v[168:169], 0, s[40:41]
	global_load_dwordx4 v[138:141], v[202:203], off
	global_load_dwordx4 v[142:145], v[204:205], off
	global_load_dwordx4 v[130:133], v[204:205], off offset:16
	global_load_dwordx4 v[134:137], v[202:203], off offset:16
	ds_read2_b32 v[208:209], v219 offset1:16
	v_lshlrev_b64 v[184:185], 12, v[184:185]
	v_lshlrev_b64 v[186:187], 12, v[186:187]
	v_lshl_add_u64 v[206:207], v[170:171], 0, v[184:185]
	v_lshl_add_u64 v[200:201], v[170:171], 0, v[186:187]
	s_waitcnt lgkmcnt(0)
	v_pk_mul_f32 v[210:211], v[32:33], v[208:209] op_sel_hi:[1,0]
	v_pk_mul_f32 v[212:213], v[30:31], v[208:209] op_sel_hi:[1,0]
	v_pk_mul_f32 v[214:215], v[28:29], v[208:209] op_sel_hi:[1,0]
	v_pk_mul_f32 v[228:229], v[26:27], v[208:209] op_sel_hi:[1,0]
	v_mov_b32_e32 v208, v209
	v_pk_mul_f32 v[230:231], v[48:49], v[208:209] op_sel_hi:[1,0]
	v_pk_mul_f32 v[232:233], v[46:47], v[208:209] op_sel_hi:[1,0]
	v_pk_mul_f32 v[234:235], v[44:45], v[208:209] op_sel_hi:[1,0]
	v_pk_mul_f32 v[208:209], v[42:43], v[208:209] op_sel_hi:[1,0]
	v_lshlrev_b64 v[188:189], 12, v[188:189]
	v_lshlrev_b64 v[190:191], 12, v[190:191]
	v_lshlrev_b64 v[192:193], 12, v[192:193]
	v_lshlrev_b64 v[194:195], 12, v[194:195]
	v_lshlrev_b64 v[196:197], 12, v[196:197]
	s_lshl_b64 s[14:15], s[36:37], 14
	s_andn2_b64 vcc, exec, s[30:31]
	s_mov_b64 s[30:31], -1
	s_waitcnt vmcnt(2)
	v_pk_fma_f32 v[210:211], v[140:141], v[210:211], v[144:145]
	v_pk_fma_f32 v[212:213], v[138:139], v[212:213], v[142:143]
	s_waitcnt vmcnt(0)
	v_pk_fma_f32 v[214:215], v[136:137], v[214:215], v[132:133]
	v_pk_fma_f32 v[228:229], v[134:135], v[228:229], v[130:131]
	v_pk_fma_f32 v[230:231], v[140:141], v[230:231], v[144:145]
	v_pk_fma_f32 v[232:233], v[138:139], v[232:233], v[142:143]
	v_pk_fma_f32 v[234:235], v[136:137], v[234:235], v[132:133]
	v_pk_fma_f32 v[236:237], v[134:135], v[208:209], v[130:131]
	v_cvt_pk_bf16_f32 v208, v212, v213
	v_cvt_pk_bf16_f32 v209, v210, v211
	v_cvt_pk_bf16_f32 v210, v228, v229
	v_cvt_pk_bf16_f32 v211, v214, v215
	v_cvt_pk_bf16_f32 v212, v232, v233
	v_cvt_pk_bf16_f32 v213, v230, v231
	v_cvt_pk_bf16_f32 v214, v236, v237
	v_cvt_pk_bf16_f32 v215, v234, v235
	global_store_dwordx4 v[206:207], v[208:211], off
	global_store_dwordx4 v[200:201], v[212:215], off
	ds_read2_b32 v[212:213], v219 offset0:32 offset1:48
	v_lshl_add_u64 v[210:211], v[170:171], 0, v[188:189]
	v_lshl_add_u64 v[208:209], v[170:171], 0, v[190:191]
	s_waitcnt lgkmcnt(0)
	v_pk_mul_f32 v[214:215], v[64:65], v[212:213] op_sel_hi:[1,0]
	v_pk_mul_f32 v[228:229], v[62:63], v[212:213] op_sel_hi:[1,0]
	v_pk_mul_f32 v[230:231], v[60:61], v[212:213] op_sel_hi:[1,0]
	v_pk_mul_f32 v[232:233], v[58:59], v[212:213] op_sel_hi:[1,0]
	v_mov_b32_e32 v212, v213
	v_pk_fma_f32 v[214:215], v[140:141], v[214:215], v[144:145]
	v_pk_fma_f32 v[228:229], v[138:139], v[228:229], v[142:143]
	v_pk_fma_f32 v[230:231], v[136:137], v[230:231], v[132:133]
	v_pk_fma_f32 v[232:233], v[134:135], v[232:233], v[130:131]
	v_pk_mul_f32 v[234:235], v[96:97], v[212:213] op_sel_hi:[1,0]
	v_pk_mul_f32 v[236:237], v[94:95], v[212:213] op_sel_hi:[1,0]
	v_pk_mul_f32 v[238:239], v[92:93], v[212:213] op_sel_hi:[1,0]
	v_pk_mul_f32 v[240:241], v[90:91], v[212:213] op_sel_hi:[1,0]
	v_cvt_pk_bf16_f32 v212, v228, v229
	v_cvt_pk_bf16_f32 v213, v214, v215
	v_cvt_pk_bf16_f32 v214, v232, v233
	v_cvt_pk_bf16_f32 v215, v230, v231
	v_pk_fma_f32 v[228:229], v[140:141], v[234:235], v[144:145]
	v_pk_fma_f32 v[230:231], v[138:139], v[236:237], v[142:143]
	v_pk_fma_f32 v[232:233], v[136:137], v[238:239], v[132:133]
	v_pk_fma_f32 v[234:235], v[134:135], v[240:241], v[130:131]
	global_store_dwordx4 v[210:211], v[212:215], off
	s_nop 1
	v_cvt_pk_bf16_f32 v212, v230, v231
	v_cvt_pk_bf16_f32 v213, v228, v229
	v_cvt_pk_bf16_f32 v214, v234, v235
	v_cvt_pk_bf16_f32 v215, v232, v233
	global_store_dwordx4 v[208:209], v[212:215], off
	ds_read2_b32 v[214:215], v219 offset0:128 offset1:144
	s_waitcnt lgkmcnt(0)
	v_pk_mul_f32 v[228:229], v[116:117], v[214:215] op_sel_hi:[1,0]
	v_pk_mul_f32 v[230:231], v[114:115], v[214:215] op_sel_hi:[1,0]
	v_pk_mul_f32 v[232:233], v[112:113], v[214:215] op_sel_hi:[1,0]
	v_pk_mul_f32 v[234:235], v[110:111], v[214:215] op_sel_hi:[1,0]
	v_mov_b32_e32 v214, v215
	v_pk_fma_f32 v[236:237], v[140:141], v[228:229], v[144:145]
	v_pk_fma_f32 v[228:229], v[138:139], v[230:231], v[142:143]
	v_pk_fma_f32 v[232:233], v[136:137], v[232:233], v[132:133]
	v_pk_fma_f32 v[230:231], v[134:135], v[234:235], v[130:131]
	v_pk_mul_f32 v[234:235], v[128:129], v[214:215] op_sel_hi:[1,0]
	v_pk_mul_f32 v[238:239], v[126:127], v[214:215] op_sel_hi:[1,0]
	v_pk_mul_f32 v[240:241], v[124:125], v[214:215] op_sel_hi:[1,0]
	v_pk_mul_f32 v[214:215], v[122:123], v[214:215] op_sel_hi:[1,0]
	v_lshl_add_u64 v[212:213], v[170:171], 0, v[192:193]
	v_cvt_pk_bf16_f32 v228, v228, v229
	v_cvt_pk_bf16_f32 v229, v236, v237
	v_cvt_pk_bf16_f32 v230, v230, v231
	v_cvt_pk_bf16_f32 v231, v232, v233
	v_pk_fma_f32 v[232:233], v[140:141], v[234:235], v[144:145]
	v_pk_fma_f32 v[234:235], v[138:139], v[238:239], v[142:143]
	v_pk_fma_f32 v[236:237], v[136:137], v[240:241], v[132:133]
	v_pk_fma_f32 v[214:215], v[134:135], v[214:215], v[130:131]
	global_store_dwordx4 v[212:213], v[228:231], off
	s_nop 1
	v_cvt_pk_bf16_f32 v228, v234, v235
	v_cvt_pk_bf16_f32 v229, v232, v233
	v_cvt_pk_bf16_f32 v230, v214, v215
	v_cvt_pk_bf16_f32 v231, v236, v237
	v_lshl_add_u64 v[214:215], v[170:171], 0, v[194:195]
	global_store_dwordx4 v[214:215], v[228:231], off
	ds_read2_b32 v[232:233], v219 offset0:160 offset1:176
	s_waitcnt lgkmcnt(0)
	v_pk_mul_f32 v[234:235], v[108:109], v[232:233] op_sel_hi:[1,0]
	v_pk_mul_f32 v[228:229], v[120:121], v[232:233] op_sel_hi:[1,0]
	v_pk_mul_f32 v[230:231], v[118:119], v[232:233] op_sel_hi:[1,0]
	v_pk_fma_f32 v[236:237], v[140:141], v[228:229], v[144:145]
	v_pk_fma_f32 v[228:229], v[138:139], v[230:231], v[142:143]
	v_pk_mul_f32 v[230:231], v[106:107], v[232:233] op_sel_hi:[1,0]
	v_pk_fma_f32 v[234:235], v[136:137], v[234:235], v[132:133]
	v_pk_fma_f32 v[230:231], v[134:135], v[230:231], v[130:131]
	v_cvt_pk_bf16_f32 v228, v228, v229
	v_cvt_pk_bf16_f32 v229, v236, v237
	v_cvt_pk_bf16_f32 v230, v230, v231
	v_cvt_pk_bf16_f32 v231, v234, v235
	v_lshl_add_u64 v[236:237], v[170:171], 0, v[196:197]
	global_store_dwordx4 v[236:237], v[228:231], off
	s_nop 1
	v_mov_b32_e32 v228, v233
	v_pk_mul_f32 v[230:231], v[80:81], v[228:229] op_sel_hi:[1,0]
	v_pk_mul_f32 v[232:233], v[78:79], v[228:229] op_sel_hi:[1,0]
	v_pk_fma_f32 v[140:141], v[140:141], v[230:231], v[144:145]
	v_pk_mul_f32 v[144:145], v[74:75], v[228:229] op_sel_hi:[1,0]
	v_pk_fma_f32 v[138:139], v[138:139], v[232:233], v[142:143]
	v_pk_mul_f32 v[142:143], v[76:77], v[228:229] op_sel_hi:[1,0]
	v_pk_fma_f32 v[130:131], v[134:135], v[144:145], v[130:131]
	v_pk_fma_f32 v[136:137], v[136:137], v[142:143], v[132:133]
	v_cvt_pk_bf16_f32 v134, v130, v131
	v_lshlrev_b64 v[130:131], 12, v[198:199]
	v_cvt_pk_bf16_f32 v132, v138, v139
	v_cvt_pk_bf16_f32 v133, v140, v141
	v_cvt_pk_bf16_f32 v135, v136, v137
	v_lshl_add_u64 v[144:145], v[170:171], 0, v[130:131]
	global_store_dwordx4 v[144:145], v[132:135], off
	global_load_dwordx4 v[132:135], v[204:205], off offset:512
	global_load_dwordx4 v[136:139], v[202:203], off offset:512
	global_load_dwordx4 v[140:143], v[202:203], off offset:528
	s_nop 0
	global_load_dwordx4 v[202:205], v[204:205], off offset:528
	ds_read2_b32 v[198:199], v219 offset1:16
	s_waitcnt lgkmcnt(0)
	v_pk_mul_f32 v[228:229], v[4:5], v[198:199] op_sel_hi:[1,0]
	v_pk_mul_f32 v[230:231], v[2:3], v[198:199] op_sel_hi:[1,0]
	v_pk_mul_f32 v[232:233], v[8:9], v[198:199] op_sel_hi:[1,0]
	v_pk_mul_f32 v[234:235], v[6:7], v[198:199] op_sel_hi:[1,0]
	v_mov_b32_e32 v198, v199
	v_pk_mul_f32 v[238:239], v[12:13], v[198:199] op_sel_hi:[1,0]
	v_pk_mul_f32 v[240:241], v[10:11], v[198:199] op_sel_hi:[1,0]
	v_pk_mul_f32 v[242:243], v[16:17], v[198:199] op_sel_hi:[1,0]
	v_pk_mul_f32 v[198:199], v[14:15], v[198:199] op_sel_hi:[1,0]
	s_waitcnt vmcnt(2)
	v_pk_fma_f32 v[244:245], v[138:139], v[228:229], v[134:135]
	v_pk_fma_f32 v[228:229], v[136:137], v[230:231], v[132:133]
	s_waitcnt vmcnt(0)
	v_pk_fma_f32 v[232:233], v[142:143], v[232:233], v[204:205]
	v_pk_fma_f32 v[230:231], v[140:141], v[234:235], v[202:203]
	v_pk_fma_f32 v[234:235], v[138:139], v[238:239], v[134:135]
	v_pk_fma_f32 v[238:239], v[136:137], v[240:241], v[132:133]
	v_pk_fma_f32 v[240:241], v[142:143], v[242:243], v[204:205]
	v_pk_fma_f32 v[198:199], v[140:141], v[198:199], v[202:203]
	v_cvt_pk_bf16_f32 v228, v228, v229
	v_cvt_pk_bf16_f32 v229, v244, v245
	v_cvt_pk_bf16_f32 v230, v230, v231
	v_cvt_pk_bf16_f32 v231, v232, v233
	v_cvt_pk_bf16_f32 v232, v238, v239
	v_cvt_pk_bf16_f32 v233, v234, v235
	v_cvt_pk_bf16_f32 v234, v198, v199
	v_cvt_pk_bf16_f32 v235, v240, v241
	global_store_dwordx4 v[206:207], v[228:231], off offset:256
	global_store_dwordx4 v[200:201], v[232:235], off offset:256
	ds_read2_b32 v[198:199], v219 offset0:32 offset1:48
	s_waitcnt lgkmcnt(0)
	v_pk_mul_f32 v[200:201], v[20:21], v[198:199] op_sel_hi:[1,0]
	v_pk_mul_f32 v[206:207], v[18:19], v[198:199] op_sel_hi:[1,0]
	v_pk_mul_f32 v[228:229], v[24:25], v[198:199] op_sel_hi:[1,0]
	v_pk_mul_f32 v[230:231], v[22:23], v[198:199] op_sel_hi:[1,0]
	v_mov_b32_e32 v198, v199
	v_pk_fma_f32 v[200:201], v[138:139], v[200:201], v[134:135]
	v_pk_fma_f32 v[206:207], v[136:137], v[206:207], v[132:133]
	v_pk_fma_f32 v[228:229], v[142:143], v[228:229], v[204:205]
	v_pk_fma_f32 v[230:231], v[140:141], v[230:231], v[202:203]
	v_pk_mul_f32 v[232:233], v[36:37], v[198:199] op_sel_hi:[1,0]
	v_pk_mul_f32 v[234:235], v[34:35], v[198:199] op_sel_hi:[1,0]
	v_pk_mul_f32 v[238:239], v[40:41], v[198:199] op_sel_hi:[1,0]
	v_pk_mul_f32 v[240:241], v[38:39], v[198:199] op_sel_hi:[1,0]
	v_cvt_pk_bf16_f32 v198, v206, v207
	v_cvt_pk_bf16_f32 v199, v200, v201
	v_cvt_pk_bf16_f32 v200, v230, v231
	v_cvt_pk_bf16_f32 v201, v228, v229
	v_pk_fma_f32 v[206:207], v[138:139], v[232:233], v[134:135]
	v_pk_fma_f32 v[228:229], v[136:137], v[234:235], v[132:133]
	v_pk_fma_f32 v[230:231], v[142:143], v[238:239], v[204:205]
	v_pk_fma_f32 v[232:233], v[140:141], v[240:241], v[202:203]
	global_store_dwordx4 v[210:211], v[198:201], off offset:256
	s_nop 1
	v_cvt_pk_bf16_f32 v198, v228, v229
	v_cvt_pk_bf16_f32 v199, v206, v207
	v_cvt_pk_bf16_f32 v200, v232, v233
	v_cvt_pk_bf16_f32 v201, v230, v231
	global_store_dwordx4 v[208:209], v[198:201], off offset:256
	ds_read2_b32 v[198:199], v219 offset0:128 offset1:144
	s_waitcnt lgkmcnt(0)
	v_pk_mul_f32 v[206:207], v[50:51], v[198:199] op_sel_hi:[1,0]
	v_pk_mul_f32 v[200:201], v[52:53], v[198:199] op_sel_hi:[1,0]
	v_pk_mul_f32 v[208:209], v[56:57], v[198:199] op_sel_hi:[1,0]
	v_pk_mul_f32 v[210:211], v[54:55], v[198:199] op_sel_hi:[1,0]
	v_mov_b32_e32 v228, v199
	v_pk_fma_f32 v[200:201], v[138:139], v[200:201], v[134:135]
	v_pk_fma_f32 v[198:199], v[136:137], v[206:207], v[132:133]
	v_pk_fma_f32 v[206:207], v[142:143], v[208:209], v[204:205]
	v_pk_fma_f32 v[208:209], v[140:141], v[210:211], v[202:203]
	v_cvt_pk_bf16_f32 v198, v198, v199
	v_cvt_pk_bf16_f32 v199, v200, v201
	v_cvt_pk_bf16_f32 v200, v208, v209
	v_cvt_pk_bf16_f32 v201, v206, v207
	v_pk_mul_f32 v[210:211], v[84:85], v[228:229] op_sel_hi:[1,0]
	v_pk_mul_f32 v[230:231], v[82:83], v[228:229] op_sel_hi:[1,0]
	global_store_dwordx4 v[212:213], v[198:201], off offset:256
	v_pk_fma_f32 v[206:207], v[138:139], v[210:211], v[134:135]
	v_pk_fma_f32 v[208:209], v[136:137], v[230:231], v[132:133]
	v_pk_mul_f32 v[198:199], v[88:89], v[228:229] op_sel_hi:[1,0]
	v_pk_mul_f32 v[200:201], v[86:87], v[228:229] op_sel_hi:[1,0]
	v_pk_fma_f32 v[210:211], v[142:143], v[198:199], v[204:205]
	v_pk_fma_f32 v[200:201], v[140:141], v[200:201], v[202:203]
	v_cvt_pk_bf16_f32 v198, v208, v209
	v_cvt_pk_bf16_f32 v199, v206, v207
	v_cvt_pk_bf16_f32 v200, v200, v201
	v_cvt_pk_bf16_f32 v201, v210, v211
	global_store_dwordx4 v[214:215], v[198:201], off offset:256
	ds_read2_b32 v[206:207], v219 offset0:160 offset1:176
	s_waitcnt lgkmcnt(0)
	v_pk_mul_f32 v[210:211], v[98:99], v[206:207] op_sel_hi:[1,0]
	v_pk_mul_f32 v[198:199], v[104:105], v[206:207] op_sel_hi:[1,0]
	v_pk_mul_f32 v[200:201], v[102:103], v[206:207] op_sel_hi:[1,0]
	v_pk_fma_f32 v[208:209], v[138:139], v[198:199], v[134:135]
	v_pk_fma_f32 v[198:199], v[136:137], v[200:201], v[132:133]
	v_pk_mul_f32 v[200:201], v[100:101], v[206:207] op_sel_hi:[1,0]
	v_cvt_pk_bf16_f32 v198, v198, v199
	v_pk_fma_f32 v[212:213], v[142:143], v[200:201], v[204:205]
	v_pk_fma_f32 v[200:201], v[140:141], v[210:211], v[202:203]
	v_cvt_pk_bf16_f32 v199, v208, v209
	v_cvt_pk_bf16_f32 v200, v200, v201
	v_cvt_pk_bf16_f32 v201, v212, v213
	global_store_dwordx4 v[236:237], v[198:201], off offset:256
	s_nop 1
	v_mov_b32_e32 v198, v207
	v_pk_mul_f32 v[200:201], v[72:73], v[198:199] op_sel_hi:[1,0]
	v_pk_mul_f32 v[206:207], v[70:71], v[198:199] op_sel_hi:[1,0]
	v_pk_fma_f32 v[134:135], v[138:139], v[200:201], v[134:135]
	v_pk_fma_f32 v[132:133], v[136:137], v[206:207], v[132:133]
	v_pk_mul_f32 v[136:137], v[68:69], v[198:199] op_sel_hi:[1,0]
	v_pk_mul_f32 v[138:139], v[66:67], v[198:199] op_sel_hi:[1,0]
	v_pk_fma_f32 v[136:137], v[142:143], v[136:137], v[204:205]
	v_pk_fma_f32 v[138:139], v[140:141], v[138:139], v[202:203]
	v_cvt_pk_bf16_f32 v132, v132, v133
	v_cvt_pk_bf16_f32 v133, v134, v135
	v_cvt_pk_bf16_f32 v134, v138, v139
	v_cvt_pk_bf16_f32 v135, v136, v137
	global_store_dwordx4 v[144:145], v[132:135], off offset:256
	v_lshl_add_u64 v[204:205], v[174:175], 0, s[14:15]
	v_lshl_add_u64 v[202:203], v[172:173], 0, s[34:35]
	global_load_dwordx4 v[134:137], v[204:205], off
	global_load_dwordx4 v[138:141], v[202:203], off
	global_load_dwordx4 v[142:145], v[202:203], off offset:16
	global_load_dwordx4 v[198:201], v[204:205], off offset:16
	ds_read2_b32 v[206:207], v219 offset1:16
	v_lshl_add_u64 v[132:133], v[176:177], 0, v[184:185]
	v_lshl_add_u64 v[184:185], v[176:177], 0, v[186:187]
	s_waitcnt lgkmcnt(0)
	v_pk_mul_f32 v[32:33], v[32:33], v[206:207] op_sel_hi:[1,0]
	v_pk_mul_f32 v[30:31], v[30:31], v[206:207] op_sel_hi:[1,0]
	v_pk_mul_f32 v[28:29], v[28:29], v[206:207] op_sel_hi:[1,0]
	v_pk_mul_f32 v[26:27], v[26:27], v[206:207] op_sel_hi:[1,0]
	v_mov_b32_e32 v186, v207
	v_pk_mul_f32 v[48:49], v[48:49], v[186:187] op_sel_hi:[1,0]
	v_pk_mul_f32 v[46:47], v[46:47], v[186:187] op_sel_hi:[1,0]
	v_pk_mul_f32 v[44:45], v[44:45], v[186:187] op_sel_hi:[1,0]
	v_pk_mul_f32 v[42:43], v[42:43], v[186:187] op_sel_hi:[1,0]
	s_waitcnt vmcnt(2)
	v_pk_fma_f32 v[32:33], v[140:141], v[32:33], v[136:137]
	v_pk_fma_f32 v[30:31], v[138:139], v[30:31], v[134:135]
	s_waitcnt vmcnt(0)
	v_pk_fma_f32 v[186:187], v[144:145], v[28:29], v[200:201]
	v_pk_fma_f32 v[28:29], v[142:143], v[26:27], v[198:199]
	v_pk_fma_f32 v[48:49], v[140:141], v[48:49], v[136:137]
	v_pk_fma_f32 v[46:47], v[138:139], v[46:47], v[134:135]
	v_pk_fma_f32 v[44:45], v[144:145], v[44:45], v[200:201]
	v_pk_fma_f32 v[42:43], v[142:143], v[42:43], v[198:199]
	v_cvt_pk_bf16_f32 v26, v30, v31
	v_cvt_pk_bf16_f32 v27, v32, v33
	v_cvt_pk_bf16_f32 v28, v28, v29
	v_cvt_pk_bf16_f32 v29, v186, v187
	v_cvt_pk_bf16_f32 v30, v46, v47
	v_cvt_pk_bf16_f32 v31, v48, v49
	v_cvt_pk_bf16_f32 v32, v42, v43
	v_cvt_pk_bf16_f32 v33, v44, v45
	global_store_dwordx4 v[132:133], v[26:29], off
	global_store_dwordx4 v[184:185], v[30:33], off
	ds_read2_b32 v[26:27], v219 offset0:32 offset1:48
	v_lshl_add_u64 v[186:187], v[176:177], 0, v[188:189]
	v_lshl_add_u64 v[188:189], v[176:177], 0, v[190:191]
	s_waitcnt lgkmcnt(0)
	v_pk_mul_f32 v[28:29], v[64:65], v[26:27] op_sel_hi:[1,0]
	v_pk_mul_f32 v[30:31], v[62:63], v[26:27] op_sel_hi:[1,0]
	v_pk_mul_f32 v[32:33], v[60:61], v[26:27] op_sel_hi:[1,0]
	v_pk_mul_f32 v[42:43], v[58:59], v[26:27] op_sel_hi:[1,0]
	v_mov_b32_e32 v26, v27
	v_pk_fma_f32 v[28:29], v[140:141], v[28:29], v[136:137]
	v_pk_fma_f32 v[30:31], v[138:139], v[30:31], v[134:135]
	v_pk_fma_f32 v[32:33], v[144:145], v[32:33], v[200:201]
	v_pk_fma_f32 v[42:43], v[142:143], v[42:43], v[198:199]
	v_pk_mul_f32 v[44:45], v[96:97], v[26:27] op_sel_hi:[1,0]
	v_pk_mul_f32 v[46:47], v[94:95], v[26:27] op_sel_hi:[1,0]
	v_pk_mul_f32 v[48:49], v[92:93], v[26:27] op_sel_hi:[1,0]
	v_pk_mul_f32 v[58:59], v[90:91], v[26:27] op_sel_hi:[1,0]
	v_cvt_pk_bf16_f32 v26, v30, v31
	v_cvt_pk_bf16_f32 v27, v28, v29
	v_cvt_pk_bf16_f32 v28, v42, v43
	v_cvt_pk_bf16_f32 v29, v32, v33
	v_pk_fma_f32 v[30:31], v[140:141], v[44:45], v[136:137]
	v_pk_fma_f32 v[32:33], v[138:139], v[46:47], v[134:135]
	v_pk_fma_f32 v[42:43], v[144:145], v[48:49], v[200:201]
	v_pk_fma_f32 v[44:45], v[142:143], v[58:59], v[198:199]
	global_store_dwordx4 v[186:187], v[26:29], off
	v_lshl_add_u64 v[58:59], v[176:177], 0, v[192:193]
	v_lshl_add_u64 v[60:61], v[176:177], 0, v[194:195]
	v_cvt_pk_bf16_f32 v26, v32, v33
	v_cvt_pk_bf16_f32 v27, v30, v31
	v_cvt_pk_bf16_f32 v28, v44, v45
	v_cvt_pk_bf16_f32 v29, v42, v43
	global_store_dwordx4 v[188:189], v[26:29], off
	ds_read2_b32 v[30:31], v219 offset0:128 offset1:144
	v_lshl_add_u64 v[62:63], v[176:177], 0, v[196:197]
	v_lshl_add_u64 v[64:65], v[176:177], 0, v[130:131]
	s_waitcnt lgkmcnt(0)
	v_pk_mul_f32 v[26:27], v[116:117], v[30:31] op_sel_hi:[1,0]
	v_pk_mul_f32 v[28:29], v[114:115], v[30:31] op_sel_hi:[1,0]
	v_pk_mul_f32 v[32:33], v[112:113], v[30:31] op_sel_hi:[1,0]
	v_pk_mul_f32 v[42:43], v[110:111], v[30:31] op_sel_hi:[1,0]
	v_pk_fma_f32 v[44:45], v[140:141], v[26:27], v[136:137]
	v_pk_fma_f32 v[26:27], v[138:139], v[28:29], v[134:135]
	v_pk_fma_f32 v[32:33], v[144:145], v[32:33], v[200:201]
	v_pk_fma_f32 v[28:29], v[142:143], v[42:43], v[198:199]
	v_cvt_pk_bf16_f32 v26, v26, v27
	v_cvt_pk_bf16_f32 v27, v44, v45
	v_cvt_pk_bf16_f32 v28, v28, v29
	v_cvt_pk_bf16_f32 v29, v32, v33
	global_store_dwordx4 v[58:59], v[26:29], off
	s_nop 1
	v_mov_b32_e32 v26, v31
	v_pk_mul_f32 v[28:29], v[128:129], v[26:27] op_sel_hi:[1,0]
	v_pk_mul_f32 v[30:31], v[126:127], v[26:27] op_sel_hi:[1,0]
	v_pk_mul_f32 v[32:33], v[124:125], v[26:27] op_sel_hi:[1,0]
	v_pk_mul_f32 v[26:27], v[122:123], v[26:27] op_sel_hi:[1,0]
	v_pk_fma_f32 v[28:29], v[140:141], v[28:29], v[136:137]
	v_pk_fma_f32 v[30:31], v[138:139], v[30:31], v[134:135]
	v_pk_fma_f32 v[32:33], v[144:145], v[32:33], v[200:201]
	v_pk_fma_f32 v[42:43], v[142:143], v[26:27], v[198:199]
	v_cvt_pk_bf16_f32 v26, v30, v31
	v_cvt_pk_bf16_f32 v27, v28, v29
	v_cvt_pk_bf16_f32 v28, v42, v43
	v_cvt_pk_bf16_f32 v29, v32, v33
	global_store_dwordx4 v[60:61], v[26:29], off
	ds_read2_b32 v[30:31], v219 offset0:160 offset1:176
	s_waitcnt lgkmcnt(0)
	v_pk_mul_f32 v[42:43], v[106:107], v[30:31] op_sel_hi:[1,0]
	v_pk_mul_f32 v[26:27], v[120:121], v[30:31] op_sel_hi:[1,0]
	v_pk_mul_f32 v[28:29], v[118:119], v[30:31] op_sel_hi:[1,0]
	v_pk_fma_f32 v[32:33], v[140:141], v[26:27], v[136:137]
	v_pk_fma_f32 v[26:27], v[138:139], v[28:29], v[134:135]
	v_pk_mul_f32 v[28:29], v[108:109], v[30:31] op_sel_hi:[1,0]
	v_cvt_pk_bf16_f32 v26, v26, v27
	v_pk_fma_f32 v[44:45], v[144:145], v[28:29], v[200:201]
	v_pk_fma_f32 v[28:29], v[142:143], v[42:43], v[198:199]
	v_cvt_pk_bf16_f32 v27, v32, v33
	v_cvt_pk_bf16_f32 v28, v28, v29
	v_cvt_pk_bf16_f32 v29, v44, v45
	global_store_dwordx4 v[62:63], v[26:29], off
	s_nop 1
	v_mov_b32_e32 v26, v31
	v_pk_mul_f32 v[28:29], v[80:81], v[26:27] op_sel_hi:[1,0]
	v_pk_mul_f32 v[30:31], v[78:79], v[26:27] op_sel_hi:[1,0]
	v_pk_mul_f32 v[32:33], v[76:77], v[26:27] op_sel_hi:[1,0]
	v_pk_mul_f32 v[26:27], v[74:75], v[26:27] op_sel_hi:[1,0]
	v_pk_fma_f32 v[28:29], v[140:141], v[28:29], v[136:137]
	v_pk_fma_f32 v[30:31], v[138:139], v[30:31], v[134:135]
	v_pk_fma_f32 v[32:33], v[144:145], v[32:33], v[200:201]
	v_pk_fma_f32 v[42:43], v[142:143], v[26:27], v[198:199]
	v_cvt_pk_bf16_f32 v26, v30, v31
	v_cvt_pk_bf16_f32 v27, v28, v29
	v_cvt_pk_bf16_f32 v28, v42, v43
	v_cvt_pk_bf16_f32 v29, v32, v33
	global_store_dwordx4 v[64:65], v[26:29], off
	global_load_dwordx4 v[26:29], v[204:205], off offset:512
	global_load_dwordx4 v[30:33], v[202:203], off offset:512
	global_load_dwordx4 v[42:45], v[202:203], off offset:528
	global_load_dwordx4 v[46:49], v[204:205], off offset:528
	ds_read2_b32 v[74:75], v219 offset1:16
	s_waitcnt lgkmcnt(0)
	v_pk_mul_f32 v[4:5], v[4:5], v[74:75] op_sel_hi:[1,0]
	v_pk_mul_f32 v[2:3], v[2:3], v[74:75] op_sel_hi:[1,0]
	v_pk_mul_f32 v[8:9], v[8:9], v[74:75] op_sel_hi:[1,0]
	v_pk_mul_f32 v[6:7], v[6:7], v[74:75] op_sel_hi:[1,0]
	v_mov_b32_e32 v74, v75
	v_pk_mul_f32 v[12:13], v[12:13], v[74:75] op_sel_hi:[1,0]
	v_pk_mul_f32 v[10:11], v[10:11], v[74:75] op_sel_hi:[1,0]
	v_pk_mul_f32 v[16:17], v[16:17], v[74:75] op_sel_hi:[1,0]
	v_pk_mul_f32 v[14:15], v[14:15], v[74:75] op_sel_hi:[1,0]
	s_waitcnt vmcnt(2)
	v_pk_fma_f32 v[4:5], v[32:33], v[4:5], v[28:29]
	v_pk_fma_f32 v[2:3], v[30:31], v[2:3], v[26:27]
	s_waitcnt vmcnt(0)
	v_pk_fma_f32 v[8:9], v[44:45], v[8:9], v[48:49]
	v_pk_fma_f32 v[6:7], v[42:43], v[6:7], v[46:47]
	v_pk_fma_f32 v[12:13], v[32:33], v[12:13], v[28:29]
	v_pk_fma_f32 v[10:11], v[30:31], v[10:11], v[26:27]
	v_pk_fma_f32 v[16:17], v[44:45], v[16:17], v[48:49]
	v_pk_fma_f32 v[14:15], v[42:43], v[14:15], v[46:47]
	v_cvt_pk_bf16_f32 v2, v2, v3
	v_cvt_pk_bf16_f32 v3, v4, v5
	v_cvt_pk_bf16_f32 v4, v6, v7
	v_cvt_pk_bf16_f32 v5, v8, v9
	v_cvt_pk_bf16_f32 v6, v10, v11
	v_cvt_pk_bf16_f32 v7, v12, v13
	v_cvt_pk_bf16_f32 v8, v14, v15
	v_cvt_pk_bf16_f32 v9, v16, v17
	global_store_dwordx4 v[132:133], v[2:5], off offset:256
	global_store_dwordx4 v[184:185], v[6:9], off offset:256
	ds_read2_b32 v[2:3], v219 offset0:32 offset1:48
	s_waitcnt lgkmcnt(0)
	v_pk_mul_f32 v[4:5], v[20:21], v[2:3] op_sel_hi:[1,0]
	v_pk_mul_f32 v[6:7], v[18:19], v[2:3] op_sel_hi:[1,0]
	v_pk_mul_f32 v[8:9], v[24:25], v[2:3] op_sel_hi:[1,0]
	v_pk_mul_f32 v[10:11], v[22:23], v[2:3] op_sel_hi:[1,0]
	v_mov_b32_e32 v12, v3
	v_pk_fma_f32 v[4:5], v[32:33], v[4:5], v[28:29]
	v_pk_fma_f32 v[2:3], v[30:31], v[6:7], v[26:27]
	v_pk_fma_f32 v[6:7], v[44:45], v[8:9], v[48:49]
	v_pk_fma_f32 v[8:9], v[42:43], v[10:11], v[46:47]
	v_cvt_pk_bf16_f32 v2, v2, v3
	v_cvt_pk_bf16_f32 v3, v4, v5
	v_cvt_pk_bf16_f32 v4, v8, v9
	v_cvt_pk_bf16_f32 v5, v6, v7
	v_pk_mul_f32 v[10:11], v[36:37], v[12:13] op_sel_hi:[1,0]
	v_pk_mul_f32 v[14:15], v[34:35], v[12:13] op_sel_hi:[1,0]
	v_pk_mul_f32 v[16:17], v[40:41], v[12:13] op_sel_hi:[1,0]
	global_store_dwordx4 v[186:187], v[2:5], off offset:256
	v_pk_fma_f32 v[6:7], v[32:33], v[10:11], v[28:29]
	v_pk_fma_f32 v[8:9], v[30:31], v[14:15], v[26:27]
	v_pk_mul_f32 v[2:3], v[38:39], v[12:13] op_sel_hi:[1,0]
	v_pk_fma_f32 v[10:11], v[44:45], v[16:17], v[48:49]
	v_pk_fma_f32 v[4:5], v[42:43], v[2:3], v[46:47]
	v_cvt_pk_bf16_f32 v2, v8, v9
	v_cvt_pk_bf16_f32 v3, v6, v7
	v_cvt_pk_bf16_f32 v4, v4, v5
	v_cvt_pk_bf16_f32 v5, v10, v11
	global_store_dwordx4 v[188:189], v[2:5], off offset:256
	ds_read2_b32 v[6:7], v219 offset0:128 offset1:144
	s_waitcnt lgkmcnt(0)
	v_pk_mul_f32 v[10:11], v[54:55], v[6:7] op_sel_hi:[1,0]
	v_pk_mul_f32 v[2:3], v[52:53], v[6:7] op_sel_hi:[1,0]
	v_pk_mul_f32 v[4:5], v[50:51], v[6:7] op_sel_hi:[1,0]
	v_pk_fma_f32 v[8:9], v[32:33], v[2:3], v[28:29]
	v_pk_fma_f32 v[2:3], v[30:31], v[4:5], v[26:27]
	v_pk_mul_f32 v[4:5], v[56:57], v[6:7] op_sel_hi:[1,0]
	v_cvt_pk_bf16_f32 v2, v2, v3
	v_pk_fma_f32 v[12:13], v[44:45], v[4:5], v[48:49]
	v_pk_fma_f32 v[4:5], v[42:43], v[10:11], v[46:47]
	v_cvt_pk_bf16_f32 v3, v8, v9
	v_cvt_pk_bf16_f32 v4, v4, v5
	v_cvt_pk_bf16_f32 v5, v12, v13
	global_store_dwordx4 v[58:59], v[2:5], off offset:256
	s_nop 1
	v_mov_b32_e32 v2, v7
	v_pk_mul_f32 v[4:5], v[84:85], v[2:3] op_sel_hi:[1,0]
	v_pk_mul_f32 v[6:7], v[82:83], v[2:3] op_sel_hi:[1,0]
	v_pk_mul_f32 v[8:9], v[88:89], v[2:3] op_sel_hi:[1,0]
	v_pk_mul_f32 v[2:3], v[86:87], v[2:3] op_sel_hi:[1,0]
	v_pk_fma_f32 v[4:5], v[32:33], v[4:5], v[28:29]
	v_pk_fma_f32 v[6:7], v[30:31], v[6:7], v[26:27]
	v_pk_fma_f32 v[8:9], v[44:45], v[8:9], v[48:49]
	v_pk_fma_f32 v[10:11], v[42:43], v[2:3], v[46:47]
	v_cvt_pk_bf16_f32 v2, v6, v7
	v_cvt_pk_bf16_f32 v3, v4, v5
	v_cvt_pk_bf16_f32 v4, v10, v11
	v_cvt_pk_bf16_f32 v5, v8, v9
	global_store_dwordx4 v[60:61], v[2:5], off offset:256
	ds_read2_b32 v[6:7], v219 offset0:160 offset1:176
	s_waitcnt lgkmcnt(0)
	v_pk_mul_f32 v[10:11], v[98:99], v[6:7] op_sel_hi:[1,0]
	v_pk_mul_f32 v[2:3], v[104:105], v[6:7] op_sel_hi:[1,0]
	v_pk_mul_f32 v[4:5], v[102:103], v[6:7] op_sel_hi:[1,0]
	v_pk_fma_f32 v[8:9], v[32:33], v[2:3], v[28:29]
	v_pk_fma_f32 v[2:3], v[30:31], v[4:5], v[26:27]
	v_pk_mul_f32 v[4:5], v[100:101], v[6:7] op_sel_hi:[1,0]
	v_cvt_pk_bf16_f32 v2, v2, v3
	v_pk_fma_f32 v[12:13], v[44:45], v[4:5], v[48:49]
	v_pk_fma_f32 v[4:5], v[42:43], v[10:11], v[46:47]
	v_cvt_pk_bf16_f32 v3, v8, v9
	v_cvt_pk_bf16_f32 v4, v4, v5
	v_cvt_pk_bf16_f32 v5, v12, v13
	global_store_dwordx4 v[62:63], v[2:5], off offset:256
	s_nop 1
	v_mov_b32_e32 v2, v7
	v_pk_mul_f32 v[4:5], v[72:73], v[2:3] op_sel_hi:[1,0]
	v_pk_mul_f32 v[6:7], v[70:71], v[2:3] op_sel_hi:[1,0]
	v_pk_mul_f32 v[8:9], v[68:69], v[2:3] op_sel_hi:[1,0]
	v_pk_mul_f32 v[2:3], v[66:67], v[2:3] op_sel_hi:[1,0]
	v_pk_fma_f32 v[4:5], v[32:33], v[4:5], v[28:29]
	v_pk_fma_f32 v[6:7], v[30:31], v[6:7], v[26:27]
	v_pk_fma_f32 v[8:9], v[44:45], v[8:9], v[48:49]
	v_pk_fma_f32 v[10:11], v[42:43], v[2:3], v[46:47]
	v_cvt_pk_bf16_f32 v2, v6, v7
	v_cvt_pk_bf16_f32 v3, v4, v5
	v_cvt_pk_bf16_f32 v4, v10, v11
	v_cvt_pk_bf16_f32 v5, v8, v9
	global_store_dwordx4 v[64:65], v[2:5], off offset:256
	s_cbranch_vccnz .LBB0_873
	s_andn2_b64 vcc, exec, s[12:13]
	s_cbranch_vccnz .LBB0_872
	s_barrier
	s_branch .LBB0_872

.LBB0_1521:
	s_waitcnt lgkmcnt(0)
	s_cmp_gt_u32 s3, 63
	s_cbranch_scc1 .LBB0_1534
	s_memrealtime s[42:43]
	s_lshl_b32 s14, s36, 6
	s_ashr_i32 s15, s14, 31
	s_lshl_b64 s[14:15], s[14:15], 2
	s_add_u32 s44, s59, s14
	s_addc_u32 s45, s60, s15
	s_mov_b32 s3, 1
	s_branch .LBB0_1524
